# v33 + hgC: hg_norm gain vectors loaded once before the loop; three of the four per-item load->vmcnt(0) round trips removed
# speedup vs baseline: 1.0064x; 1.0053x over previous
; #define GAS __attribute__((address_space(1)))
; __device__ __forceinline__ void hgC_loop(Frame& F, unsigned* ctr) {
;     ...
;     if (tid == 0) { slot[0] = (int)__hip_atomic_fetch_add(ctr, 1u, __ATOMIC_RELAXED, __HIP_MEMORY_SCOPE_AGENT); slot[1] = (int)__hip_atomic_fetch_add(ctr, 1u, __ATOMIC_RELAXED, __HIP_MEMORY_SCOPE_AGENT); }
;     __syncthreads();
;     int item = slot[0], nxt = slot[1], par = 0;
;     if (item >= 1024) return;
;     v4u sc[4], qh[2], oi[2]; v2u og[4];
;     ...
;     HGC_FETCH(item);
;     ...
;           for (int q = 0; q < 4; ++q) { const int v0 = 32 * vb + 8 * q + 4 * hh; const f32x4 gn = *(const GAS f32x4*)(F.in[17] + v0);
.LBB0_690:
	s_or_b64 exec, exec, s[0:1]
	v_mov_b32_e32 v55, 0
	s_waitcnt lgkmcnt(0)
	s_barrier
	ds_read_b32 v2, v55 offset:53248
	ds_read_b32 v3, v55 offset:53252
	s_movk_i32 s0, 0x3ff
	s_mov_b32 s11, 0
	s_waitcnt lgkmcnt(1)
	v_cmp_lt_i32_e32 vcc, s0, v2
	v_readfirstlane_b32 s18, v2
	s_waitcnt lgkmcnt(0)
	v_readfirstlane_b32 s17, v3
	s_cbranch_vccnz .LBB0_701
	s_lshl_b32 s0, s96, 3
	v_and_b32_e32 v12, 31, v0
	v_readlane_b32 s20, v238, 25
	s_and_b32 s0, s0, 0x1fffffe0
	s_ashr_i32 s19, s18, 31
	s_bfe_u32 s3, s20, 0x20006
	v_or_b32_e32 v90, s0, v12
	s_lshl_b64 s[0:1], s[18:19], 15
	s_add_u32 s0, s46, s0
	v_lshlrev_b32_e32 v2, 4, v0
	v_or_b32_e32 v6, 0x200, v0
	s_addc_u32 s1, s47, s1
	v_and_b32_e32 v54, 0xf0, v2
	v_lshrrev_b32_e32 v14, 4, v6
	v_lshl_add_u64 v[2:3], s[0:1], 0, v[54:55]
	v_lshlrev_b32_e32 v56, 8, v139
	v_mov_b32_e32 v57, v55
	v_lshlrev_b32_e32 v58, 8, v14
	v_mov_b32_e32 v59, v55
	s_lshl_b64 s[14:15], s[18:19], 14
	v_lshl_add_u64 v[4:5], v[2:3], 0, v[56:57]
	v_lshl_add_u64 v[6:7], v[2:3], 0, v[58:59]
	s_add_u32 s12, s48, 0x1000000
	global_load_dwordx4 v[18:21], v[4:5], off
	global_load_dwordx4 v[22:25], v[6:7], off
	v_or_b32_e32 v6, 0x600, v0
	s_addc_u32 s13, s49, 0
	s_lshl_b32 s10, s18, 4
	s_lshl_b32 s16, s18, 6
	v_lshrrev_b32_e32 v15, 4, v6
	v_or_b32_e32 v60, 0x4000, v56
	v_mov_b32_e32 v61, v55
	v_lshlrev_b32_e32 v62, 8, v15
	v_mov_b32_e32 v63, v55
	s_add_u32 s0, s48, s14
	v_lshl_add_u64 v[4:5], v[2:3], 0, v[60:61]
	v_lshl_add_u64 v[2:3], v[2:3], 0, v[62:63]
	s_addc_u32 s1, s49, s15
	s_and_b32 s10, s10, 0xfffff800
	global_load_dwordx4 v[26:29], v[4:5], off
	global_load_dwordx4 v[30:33], v[2:3], off
	v_lshl_add_u64 v[2:3], s[0:1], 0, v[54:55]
	s_add_u32 s0, s12, s14
	v_lshl_add_u64 v[4:5], v[2:3], 0, v[56:57]
	v_lshl_add_u64 v[2:3], v[2:3], 0, v[58:59]
	s_addc_u32 s1, s13, s15
	s_and_b32 s15, s20, 0xffffffc0
	global_load_dwordx4 v[34:37], v[4:5], off
	global_load_dwordx4 v[38:41], v[2:3], off
	v_or_b32_e32 v2, s15, v154
	v_mov_b32_e32 v3, v55
	s_and_b32 s14, s16, 0x7c0
	v_lshlrev_b64 v[2:3], 5, v[2:3]
	v_lshl_add_u64 v[4:5], s[0:1], 0, v[2:3]
	s_or_b32 s0, s10, s14
	global_load_dwordx4 v[50:53], v[4:5], off offset:16
	global_load_dwordx4 v[6:9], v[4:5], off
	v_add_u32_e32 v4, s0, v90
	v_ashrrev_i32_e32 v5, 31, v4
	v_lshlrev_b64 v[4:5], 12, v[4:5]
	s_lshl_b32 s0, s18, 3
	v_lshl_add_u64 v[4:5], s[56:57], 0, v[4:5]
	s_and_b32 s10, s0, 0x300
	v_lshrrev_b32_e32 v13, 5, v154
	v_lshl_add_u64 v[4:5], v[4:5], 0, s[10:11]
	s_lshl_b32 s10, s3, 6
	v_lshl_add_u64 v[4:5], v[4:5], 0, s[10:11]
	v_lshlrev_b32_e32 v10, 3, v13
	v_mov_b32_e32 v11, v55
	v_lshl_add_u64 v[4:5], v[4:5], 0, v[10:11]
	global_load_dwordx2 v[80:81], v[4:5], off offset:3072
	global_load_dwordx2 v[78:79], v[4:5], off offset:3088
	global_load_dwordx2 v[76:77], v[4:5], off offset:3104
	global_load_dwordx2 v[70:71], v[4:5], off offset:3120
	s_lshl_b32 s10, s3, 5
	s_lshl_b32 s0, s3, 2
	v_or_b32_e32 v10, s10, v12
	s_add_i32 s3, s0, 0
	s_movk_i32 s0, 0x110
	v_mul_u32_u24_e32 v10, 0x110, v10
	v_lshlrev_b32_e32 v11, 4, v13
	v_lshlrev_b32_e32 v4, 2, v13
	v_add3_u32 v91, 0, v10, v11
	v_mul_lo_u32 v10, v90, s0
	v_add3_u32 v92, 0, v10, v11
	v_or_b32_e32 v10, s10, v4
	v_readlane_b32 s68, v238, 29
	v_add_u32_e32 v5, 0, v54
	v_mul_u32_u24_e32 v11, 0x110, v139
	v_mul_u32_u24_e32 v12, 0x110, v14
	v_mul_u32_u24_e32 v13, 0x110, v15
	v_lshl_add_u64 v[64:65], s[46:47], 0, v[54:55]
	v_lshl_add_u64 v[66:67], s[48:49], 0, v[54:55]
	v_lshl_add_u64 v[68:69], s[12:13], 0, v[2:3]
	v_lshlrev_b32_e32 v54, 2, v10
	v_readlane_b32 s70, v238, 31
	v_readlane_b32 s71, v238, 32
	v_mbcnt_lo_u32_b32 v2, -1, 0
	v_cmp_gt_u32_e64 s[0:1], 32, v154
	v_lshlrev_b32_e32 v93, 4, v90
	v_lshl_add_u64 v[72:73], s[70:71], 0, v[54:55]
	global_load_dwordx4 v[198:201], v[72:73], off
	global_load_dwordx4 v[202:205], v[72:73], off offset:32
	global_load_dwordx4 v[206:209], v[72:73], off offset:64
	global_load_dwordx4 v[210:213], v[72:73], off offset:96
	v_add_u32_e32 v94, v5, v11
	v_add_u32_e32 v95, v5, v12
	v_add_u32_e32 v96, v5, v13
	s_lshl_b32 s12, s10, 1
	v_lshlrev_b32_e32 v74, 1, v4
	v_mbcnt_hi_u32_b32 v97, -1, v2
	v_mov_b32_e32 v98, 0x358637bd
	v_lshlrev_b32_e32 v54, 1, v10
	s_mov_b64 s[14:15], 0xc500400
	s_mov_b32 s19, 0xc500000
	v_mov_b32_e32 v99, v55
	v_readlane_b32 s69, v238, 30
	v_readlane_b32 s72, v238, 33
	v_readlane_b32 s73, v238, 34
	v_readlane_b32 s74, v238, 35
	v_readlane_b32 s75, v238, 36
	v_readlane_b32 s76, v238, 37
	v_readlane_b32 s77, v238, 38
	v_readlane_b32 s78, v238, 39
	v_readlane_b32 s79, v238, 40
	v_readlane_b32 s80, v238, 41
	v_readlane_b32 s81, v238, 42
	v_readlane_b32 s82, v238, 43
	v_readlane_b32 s83, v238, 44
	s_branch .LBB0_693
; #define GAS __attribute__((address_space(1)))
; #define LAS __attribute__((address_space(3)))
; __device__ __forceinline__ unsigned pk2(float lo, float hi) { f32x2_t v = {lo, hi}; bf16x2_t h = __builtin_convertvector(v, bf16x2_t); return __builtin_bit_cast(unsigned, h); }
; __device__ __forceinline__ float siluf_(float x) { return x * __builtin_amdgcn_rcpf(1.0f + __builtin_amdgcn_exp2f(-1.4426950408889634f * x)); }
; __device__ __forceinline__ void hgC_loop(Frame& F, unsigned* ctr) {
;     ...
;         { float ss = 0.f;
; #pragma unroll
;           for (int r = 0; r < 16; ++r) ss += acc[r] * acc[r];
;           ss += __shfl_xor(ss, 32);
;           if (hh == 0) SS[t * 4 + vb] = ss; }
;         __syncthreads();
;         { const f32x4 s4 = *(const LAS f32x4*)(SS + t * 4); const float rstd = __builtin_amdgcn_rsqf(((s4.x + s4.y) + (s4.z + s4.w)) * (1.0f / HD) + EPS);
; #pragma unroll
;           for (int q = 0; q < 4; ++q) { const int v0 = 32 * vb + 8 * q + 4 * hh; const f32x4 gn = *(const GAS f32x4*)(F.in[17] + v0);
;               v2u w; w.x = pk2(acc[4 * q] * rstd * gn.x * siluf_(bflo(ogc[q].x)), acc[4 * q + 1] * rstd * gn.y * siluf_(bfhi(ogc[q].x)));
;               w.y = pk2(acc[4 * q + 2] * rstd * gn.z * siluf_(bflo(ogc[q].y)), acc[4 * q + 3] * rstd * gn.w * siluf_(bfhi(ogc[q].y)));
;               *(v2u*)(MIX + (size_t)(tok0 + t) * DM + 512 + h * HD + v0) = w; } }
.LBB0_692:
	s_or_b64 exec, exec, s[24:25]
	s_waitcnt lgkmcnt(0)
	s_barrier
	v_add_u32_e32 v75, 0, v93
	v_lshlrev_b32_e32 v104, 16, v80
	ds_read_b128 v[100:103], v75 offset:52224
	s_lshl_b32 s10, s18, 4
	s_lshl_b32 s13, s18, 6
	v_mul_f32_e32 v75, 0xbfb8aa3b, v104
	v_and_b32_e32 v105, 0xffff0000, v80
	s_and_b32 s24, s10, 0xfffff800
	s_and_b32 s13, s13, 0x7c0
	v_exp_f32_e32 v75, v75
	v_lshlrev_b32_e32 v80, 16, v81
	v_and_b32_e32 v81, 0xffff0000, v81
	v_mul_f32_e32 v106, 0xbfb8aa3b, v105
	s_or_b32 s13, s24, s13
	v_mul_f32_e32 v107, 0xbfb8aa3b, v80
	v_mul_f32_e32 v108, 0xbfb8aa3b, v81
	v_exp_f32_e32 v110, v106
	v_add_u32_e32 v106, s13, v90
	v_exp_f32_e32 v111, v107
	v_exp_f32_e32 v112, v108
	v_ashrrev_i32_e32 v107, 31, v106
	s_waitcnt lgkmcnt(0)
	v_mov_b32_e32 v108, v101
	v_mov_b32_e32 v109, v102
	v_mov_b32_e32 v101, v103
	s_lshl_b32 s18, s18, 3
	v_lshlrev_b64 v[106:107], 11, v[106:107]
	v_add_f32_e32 v75, 1.0, v75
	v_pk_add_f32 v[100:101], v[108:109], v[100:101]
	s_and_b32 s10, s18, 0x300
	v_lshl_add_u64 v[102:103], s[50:51], 0, v[106:107]
	v_rcp_f32_e32 v106, v75
	v_add_f32_e32 v75, v100, v101
	v_lshl_add_u64 v[102:103], v[102:103], 0, s[10:11]
	v_fmamk_f32 v75, v75, 0x3c000000, v98
	v_add_f32_e32 v107, 1.0, v110
	v_add_f32_e32 v110, 1.0, v111
	v_add_f32_e32 v111, 1.0, v112
	v_lshl_add_u64 v[100:101], v[102:103], 0, v[54:55]
	v_rsq_f32_e32 v102, v75
	v_rcp_f32_e32 v107, v107
	v_rcp_f32_e32 v108, v110
	v_rcp_f32_e32 v109, v111
	v_pk_mul_f32 v[2:3], v[2:3], v[102:103] op_sel_hi:[1,0]
	v_pk_mul_f32 v[4:5], v[4:5], v[102:103] op_sel_hi:[1,0]
	v_pk_mul_f32 v[104:105], v[106:107], v[104:105]
	v_pk_mul_f32 v[80:81], v[108:109], v[80:81]
	v_add_co_u32_e32 v110, vcc, s19, v100
	s_mov_b32 s18, s16
	s_nop 0
	v_addc_co_u32_e32 v111, vcc, 0, v101, vcc
	v_lshl_add_u64 v[100:101], v[100:101], 0, s[14:15]
	s_andn2_b64 vcc, exec, s[20:21]
	s_waitcnt vmcnt(0)
	v_pk_mul_f32 v[2:3], v[198:199], v[2:3]
	v_pk_mul_f32 v[4:5], v[200:201], v[4:5]
	v_pk_mul_f32 v[2:3], v[104:105], v[2:3]
	v_pk_mul_f32 v[4:5], v[80:81], v[4:5]
	v_cvt_pk_bf16_f32 v2, v2, v3
	v_cvt_pk_bf16_f32 v3, v4, v5
	global_store_dwordx2 v[110:111], v[2:3], off offset:1024
	v_lshlrev_b32_e32 v50, 16, v78
	v_and_b32_e32 v51, 0xffff0000, v78
	v_lshlrev_b32_e32 v52, 16, v79
	v_and_b32_e32 v53, 0xffff0000, v79
	v_mul_f32_e32 v75, 0xbfb8aa3b, v50
	v_mul_f32_e32 v78, 0xbfb8aa3b, v51
	v_mul_f32_e32 v79, 0xbfb8aa3b, v52
	v_mul_f32_e32 v80, 0xbfb8aa3b, v53
	v_exp_f32_e32 v75, v75
	v_exp_f32_e32 v78, v78
	v_exp_f32_e32 v79, v79
	v_exp_f32_e32 v80, v80
	v_add_f32_e32 v75, 1.0, v75
	v_add_f32_e32 v81, 1.0, v78
	v_add_f32_e32 v103, 1.0, v79
	v_add_f32_e32 v104, 1.0, v80
	v_rcp_f32_e32 v78, v75
	v_rcp_f32_e32 v79, v81
	v_rcp_f32_e32 v80, v103
	v_rcp_f32_e32 v81, v104
	v_pk_mul_f32 v[6:7], v[6:7], v[102:103] op_sel_hi:[1,0]
	v_pk_mul_f32 v[8:9], v[8:9], v[102:103] op_sel_hi:[1,0]
	v_pk_mul_f32 v[50:51], v[78:79], v[50:51]
	v_pk_mul_f32 v[52:53], v[80:81], v[52:53]
	v_pk_mul_f32 v[10:11], v[10:11], v[102:103] op_sel_hi:[1,0]
	v_pk_mul_f32 v[12:13], v[12:13], v[102:103] op_sel_hi:[1,0]
	v_pk_mul_f32 v[14:15], v[14:15], v[102:103] op_sel_hi:[1,0]
	v_pk_mul_f32 v[16:17], v[16:17], v[102:103] op_sel_hi:[1,0]
	v_cndmask_b32_e64 v75, 0, 1, s[22:23]
	v_mov_b64_e32 v[78:79], v[84:85]
	v_mov_b64_e32 v[80:81], v[82:83]
	v_xor_b32_e32 v99, v99, v75
	v_pk_mul_f32 v[2:3], v[202:203], v[6:7]
	v_pk_mul_f32 v[4:5], v[204:205], v[8:9]
	v_pk_mul_f32 v[2:3], v[50:51], v[2:3]
	v_pk_mul_f32 v[4:5], v[52:53], v[4:5]
	v_cvt_pk_bf16_f32 v2, v2, v3
	v_cvt_pk_bf16_f32 v3, v4, v5
	global_store_dwordx2 v[100:101], v[2:3], off offset:16
	v_lshlrev_b32_e32 v6, 16, v76
	v_and_b32_e32 v7, 0xffff0000, v76
	v_lshlrev_b32_e32 v8, 16, v77
	v_and_b32_e32 v9, 0xffff0000, v77
	v_mul_f32_e32 v50, 0xbfb8aa3b, v6
	v_mul_f32_e32 v51, 0xbfb8aa3b, v7
	v_mul_f32_e32 v52, 0xbfb8aa3b, v8
	v_mul_f32_e32 v53, 0xbfb8aa3b, v9
	v_exp_f32_e32 v50, v50
	v_exp_f32_e32 v51, v51
	v_exp_f32_e32 v52, v52
	v_exp_f32_e32 v53, v53
	v_add_f32_e32 v50, 1.0, v50
	v_add_f32_e32 v51, 1.0, v51
	v_add_f32_e32 v52, 1.0, v52
	v_add_f32_e32 v53, 1.0, v53
	v_rcp_f32_e32 v50, v50
	v_rcp_f32_e32 v51, v51
	v_rcp_f32_e32 v52, v52
	v_rcp_f32_e32 v53, v53
	v_mov_b64_e32 v[76:77], v[86:87]
	v_pk_mul_f32 v[6:7], v[50:51], v[6:7]
	v_pk_mul_f32 v[8:9], v[52:53], v[8:9]
	v_mov_b64_e32 v[52:53], v[44:45]
	v_mov_b64_e32 v[50:51], v[42:43]
	v_pk_mul_f32 v[2:3], v[10:11], v[206:207]
	v_pk_mul_f32 v[4:5], v[12:13], v[208:209]
	v_pk_mul_f32 v[2:3], v[6:7], v[2:3]
	v_pk_mul_f32 v[4:5], v[8:9], v[4:5]
	v_cvt_pk_bf16_f32 v2, v2, v3
	v_cvt_pk_bf16_f32 v3, v4, v5
	global_store_dwordx2 v[100:101], v[2:3], off offset:32
	v_lshlrev_b32_e32 v10, 16, v70
	v_and_b32_e32 v11, 0xffff0000, v70
	v_lshlrev_b32_e32 v12, 16, v71
	v_and_b32_e32 v13, 0xffff0000, v71
	v_mul_f32_e32 v42, 0xbfb8aa3b, v10
	v_mul_f32_e32 v43, 0xbfb8aa3b, v11
	v_mul_f32_e32 v44, 0xbfb8aa3b, v12
	v_mul_f32_e32 v45, 0xbfb8aa3b, v13
	v_exp_f32_e32 v42, v42
	v_exp_f32_e32 v43, v43
	v_exp_f32_e32 v44, v44
	v_exp_f32_e32 v45, v45
	v_add_f32_e32 v42, 1.0, v42
	v_add_f32_e32 v43, 1.0, v43
	v_add_f32_e32 v44, 1.0, v44
	v_add_f32_e32 v45, 1.0, v45
	v_rcp_f32_e32 v42, v42
	v_rcp_f32_e32 v43, v43
	v_rcp_f32_e32 v44, v44
	v_rcp_f32_e32 v45, v45
	v_mov_b64_e32 v[6:7], v[46:47]
	v_pk_mul_f32 v[10:11], v[42:43], v[10:11]
	v_mov_b64_e32 v[70:71], v[88:89]
	v_pk_mul_f32 v[12:13], v[44:45], v[12:13]
	v_mov_b64_e32 v[8:9], v[48:49]
	v_pk_mul_f32 v[2:3], v[14:15], v[210:211]
	v_pk_mul_f32 v[4:5], v[16:17], v[212:213]
	v_pk_mul_f32 v[2:3], v[10:11], v[2:3]
	v_pk_mul_f32 v[4:5], v[12:13], v[4:5]
	v_cvt_pk_bf16_f32 v2, v2, v3
	v_cvt_pk_bf16_f32 v3, v4, v5
	global_store_dwordx2 v[100:101], v[2:3], off offset:48
	s_barrier
	s_cbranch_vccz .LBB0_701
